# GEMM k-loop: LDS-DMA loads use SGPR base + 32-bit VGPR offset addressing; all per-iteration 64-bit VALU address arithmetic removed
# baseline (speedup 1.0000x reference)
.LBB0_637:
	s_and_b64 s[2:3], s[8:9], exec
	v_readlane_b32 s2, v255, 26
	v_readlane_b32 s4, v255, 30
	v_readlane_b32 s3, v255, 27
	v_readlane_b32 s5, v255, 31
	s_cselect_b32 s24, s5, s3
	s_cselect_b32 s28, s4, s2
	v_readlane_b32 s2, v255, 24
	v_readlane_b32 s4, v255, 32
	v_readlane_b32 s3, v255, 25
	v_readlane_b32 s5, v255, 33
	s_cselect_b32 s29, s5, s3
	s_cselect_b32 s34, s4, s2
	v_readlane_b32 s2, v255, 23
	v_readlane_b32 s3, v255, 43
	s_cselect_b32 s14, s3, s2
	v_readlane_b32 s2, v255, 39
	s_cselect_b32 s39, s2, 0
	v_readlane_b32 s2, v255, 18
	v_readlane_b32 s3, v255, 40
	s_cselect_b32 s44, s3, s2
	s_lshl_b32 s45, s15, 8
	s_mul_i32 s2, s15, 0xfe
	s_add_i32 s45, s45, s39
	s_lshl_b32 s6, s47, 8
	s_add_i32 s4, s2, -1
	s_cmp_eq_u32 s44, 7
	s_cselect_b64 vcc, -1, 0
	s_and_b64 s[2:3], vcc, exec
	s_cselect_b32 s2, 0, s45
	s_cselect_b32 s40, s4, 0
	s_ashr_i32 s3, s2, 31
	v_mov_b32_e32 v175, v163
	s_mul_i32 s3, s3, s14
	s_mul_hi_u32 s4, s2, s14
	s_ashr_i32 s7, s6, 31
	s_add_i32 s3, s4, s3
	s_waitcnt vmcnt(1)
	v_ashrrev_i32_e32 v10, 6, v175
	s_waitcnt vmcnt(0)
	v_bfe_u32 v14, v175, 3, 3
	s_mul_i32 s2, s2, s14
	s_mul_i32 s4, s7, s14
	s_mul_hi_u32 s5, s6, s14
	v_lshl_or_b32 v6, v10, 5, v14
	s_add_i32 s5, s5, s4
	v_and_b32_e32 v0, 63, v175
	s_lshl_b64 s[2:3], s[2:3], 1
	s_mul_i32 s4, s6, s14
	s_add_u32 s2, s28, s2
	v_lshlrev_b32_e32 v176, 4, v0
	v_add_u32_e32 v0, s40, v6
	s_addc_u32 s3, s24, s3
	s_lshl_b64 s[4:5], s[4:5], 1
	v_med3_i32 v0, v0, 0, v211
	s_add_u32 s4, s34, s4
	v_cndmask_b32_e32 v0, v6, v0, vcc
	s_addc_u32 s5, s29, s5
	v_bfe_u32 v223, v175, 4, 2
	v_mad_u64_u32 v[166:167], s[28:29], v0, s14, 0
	v_xor_b32_e32 v4, v223, v175
	v_ashrrev_i32_e32 v2, 31, v0
	v_mov_b32_e32 v0, v167
	v_mad_u64_u32 v[2:3], s[28:29], v2, s14, v[0:1]
	v_lshlrev_b32_e32 v0, 3, v4
	v_lshlrev_b32_e32 v15, 2, v10
	v_and_b32_e32 v0, 56, v0
	v_lshlrev_b32_e32 v177, 12, v10
	v_lshlrev_b32_e32 v130, 1, v0
	v_ashrrev_i32_e32 v0, 31, v10
	v_or_b32_e32 v17, v176, v177
	v_or_b32_e32 v18, 1, v15
	v_and_b32_e32 v174, 3, v10
	v_mul_lo_u32 v16, v0, s14
	v_readfirstlane_b32 s15, v17
	v_add_u32_e32 v0, 0x8000, v17
	v_lshl_or_b32 v10, v18, 3, v14
	v_mov_b32_e32 v167, v2
	v_mad_u64_u32 v[168:169], s[28:29], v6, s14, 0
	s_mov_b32 m0, s15
	v_readfirstlane_b32 s15, v0
	v_add_u32_e32 v0, s40, v10
	v_lshl_add_u64 v[2:3], v[166:167], 1, s[2:3]
	v_mov_b32_e32 v131, v1
	v_add_u32_e32 v169, v169, v16
	v_med3_i32 v0, v0, 0, v211
	v_lshl_add_u64 v[4:5], v[2:3], 0, v[130:131]
	v_lshl_add_u64 v[6:7], v[168:169], 1, s[4:5]
	v_cndmask_b32_e32 v0, v10, v0, vcc
	v_lshl_add_u64 v[8:9], v[6:7], 0, v[130:131]
	global_load_lds_dwordx4 v[4:5], off
	s_mov_b32 m0, s15
	v_lshrrev_b32_e32 v4, 1, v10
	v_mad_u64_u32 v[170:171], s[28:29], v0, s14, 0
	global_load_lds_dwordx4 v[8:9], off
	v_xor_b32_e32 v8, v4, v175
	v_ashrrev_i32_e32 v4, 31, v0
	v_mov_b32_e32 v0, v171
	v_mad_u64_u32 v[4:5], s[28:29], v4, s14, v[0:1]
	v_lshlrev_b32_e32 v0, 3, v8
	v_lshlrev_b32_e32 v178, 10, v18
	v_mov_b32_e32 v171, v4
	v_and_b32_e32 v0, 56, v0
	v_mad_u64_u32 v[172:173], s[28:29], v10, s14, 0
	v_or_b32_e32 v18, v176, v178
	v_lshl_add_u64 v[4:5], v[170:171], 1, s[2:3]
	v_lshlrev_b32_e32 v132, 1, v0
	v_mov_b32_e32 v133, v1
	v_add_u32_e32 v173, v173, v16
	v_readfirstlane_b32 s15, v18
	v_add_u32_e32 v0, 0x8000, v18
	v_lshl_add_u64 v[8:9], v[4:5], 0, v[132:133]
	v_lshl_add_u64 v[10:11], v[172:173], 1, s[4:5]
	s_mov_b32 m0, s15
	v_readfirstlane_b32 s15, v0
	s_waitcnt lgkmcnt(0)
	v_lshl_add_u64 v[12:13], v[10:11], 0, v[132:133]
	global_load_lds_dwordx4 v[8:9], off
	s_mov_b32 m0, s15
	v_or_b32_e32 v19, 2, v15
	global_load_lds_dwordx4 v[12:13], off
	v_lshl_or_b32 v12, v19, 3, v14
	v_add_u32_e32 v0, s40, v12
	v_med3_i32 v0, v0, 0, v211
	v_cndmask_b32_e32 v0, v12, v0, vcc
	v_lshrrev_b32_e32 v8, 1, v12
	v_mad_u64_u32 v[154:155], s[28:29], v0, s14, 0
	v_xor_b32_e32 v13, v8, v175
	v_ashrrev_i32_e32 v8, 31, v0
	v_mov_b32_e32 v0, v155
	v_mad_u64_u32 v[8:9], s[28:29], v8, s14, v[0:1]
	v_lshlrev_b32_e32 v0, 3, v13
	v_lshlrev_b32_e32 v179, 10, v19
	v_mov_b32_e32 v155, v8
	v_and_b32_e32 v0, 56, v0
	v_or_b32_e32 v19, v176, v179
	v_lshl_add_u64 v[8:9], v[154:155], 1, s[2:3]
	v_lshlrev_b32_e32 v0, 1, v0
	v_readfirstlane_b32 s15, v19
	v_lshl_add_u64 v[8:9], v[8:9], 0, v[0:1]
	v_mad_u64_u32 v[156:157], s[28:29], v12, s14, 0
	s_mov_b32 m0, s15
	v_add_u32_e32 v157, v157, v16
	global_load_lds_dwordx4 v[8:9], off
	v_add_u32_e32 v8, 0x8000, v19
	v_lshl_add_u64 v[12:13], v[156:157], 1, s[4:5]
	v_readfirstlane_b32 s15, v8
	v_lshl_add_u64 v[12:13], v[12:13], 0, v[0:1]
	s_mov_b32 m0, s15
	v_or_b32_e32 v15, 3, v15
	global_load_lds_dwordx4 v[12:13], off
	v_lshl_or_b32 v12, v15, 3, v14
	v_add_u32_e32 v8, s40, v12
	v_med3_i32 v8, v8, 0, v211
	v_cndmask_b32_e32 v8, v12, v8, vcc
	v_lshrrev_b32_e32 v9, 1, v12
	v_mad_u64_u32 v[158:159], s[28:29], v8, s14, 0
	v_xor_b32_e32 v13, v9, v175
	v_ashrrev_i32_e32 v9, 31, v8
	v_mov_b32_e32 v8, v159
	v_mad_u64_u32 v[8:9], s[28:29], v9, s14, v[8:9]
	v_lshlrev_b32_e32 v13, 3, v13
	v_lshlrev_b32_e32 v180, 10, v15
	v_mov_b32_e32 v159, v8
	v_and_b32_e32 v13, 56, v13
	v_or_b32_e32 v14, v176, v180
	v_lshl_add_u64 v[8:9], v[158:159], 1, s[2:3]
	v_lshlrev_b32_e32 v160, 1, v13
	v_mov_b32_e32 v161, v1
	v_readfirstlane_b32 s15, v14
	v_lshl_add_u64 v[8:9], v[8:9], 0, v[160:161]
	v_mad_u64_u32 v[164:165], s[28:29], v12, s14, 0
	s_mov_b32 m0, s15
	v_add_u32_e32 v165, v165, v16
	global_load_lds_dwordx4 v[8:9], off
	v_add_u32_e32 v8, 0x8000, v14
	s_cmpk_gt_u32 s14, 0x7f
	v_lshl_add_u64 v[12:13], v[164:165], 1, s[4:5]
	v_readfirstlane_b32 s15, v8
	s_cselect_b32 s34, 0x80, 0
	v_add_u32_e32 v8, 0x10000, v17
	v_lshl_add_u64 v[12:13], v[12:13], 0, v[160:161]
	s_mov_b32 m0, s15
	v_lshl_add_u64 v[2:3], v[2:3], 0, s[34:35]
	v_readfirstlane_b32 s15, v8
	global_load_lds_dwordx4 v[12:13], off
	v_lshl_add_u64 v[2:3], v[2:3], 0, v[130:131]
	s_mov_b32 m0, s15
	v_mov_b32_e32 v127, 0
	v_mov_b32_e32 v128, 0
	v_mov_b32_e32 v129, 0
	v_mov_b32_e32 v122, 0
	v_mov_b32_e32 v123, 0
	v_mov_b32_e32 v124, 0
	v_mov_b32_e32 v125, 0
	v_mov_b32_e32 v118, 0
	v_mov_b32_e32 v119, 0
	v_mov_b32_e32 v120, 0
	v_mov_b32_e32 v121, 0
	v_mov_b32_e32 v114, 0
	v_mov_b32_e32 v115, 0
	v_mov_b32_e32 v116, 0
	v_mov_b32_e32 v117, 0
	v_mov_b32_e32 v110, 0
	v_mov_b32_e32 v111, 0
	v_mov_b32_e32 v112, 0
	v_mov_b32_e32 v113, 0
	v_mov_b32_e32 v106, 0
	v_mov_b32_e32 v107, 0
	v_mov_b32_e32 v108, 0
	v_mov_b32_e32 v109, 0
	v_mov_b32_e32 v102, 0
	v_mov_b32_e32 v103, 0
	v_mov_b32_e32 v104, 0
	v_mov_b32_e32 v105, 0
	v_mov_b32_e32 v98, 0
	v_mov_b32_e32 v99, 0
	v_mov_b32_e32 v100, 0
	v_mov_b32_e32 v101, 0
	v_mov_b32_e32 v94, 0
	v_mov_b32_e32 v95, 0
	v_mov_b32_e32 v96, 0
	v_mov_b32_e32 v97, 0
	v_mov_b32_e32 v90, 0
	v_mov_b32_e32 v91, 0
	v_mov_b32_e32 v92, 0
	v_mov_b32_e32 v93, 0
	v_mov_b32_e32 v86, 0
	v_mov_b32_e32 v87, 0
	v_mov_b32_e32 v88, 0
	v_mov_b32_e32 v89, 0
	v_mov_b32_e32 v82, 0
	v_mov_b32_e32 v83, 0
	v_mov_b32_e32 v84, 0
	v_mov_b32_e32 v85, 0
	v_mov_b32_e32 v78, 0
	v_mov_b32_e32 v79, 0
	v_mov_b32_e32 v80, 0
	v_mov_b32_e32 v81, 0
	v_mov_b32_e32 v74, 0
	v_mov_b32_e32 v75, 0
	v_mov_b32_e32 v76, 0
	v_mov_b32_e32 v77, 0
	v_mov_b32_e32 v70, 0
	v_mov_b32_e32 v71, 0
	v_mov_b32_e32 v72, 0
	v_mov_b32_e32 v73, 0
	v_mov_b32_e32 v66, 0
	v_mov_b32_e32 v67, 0
	v_mov_b32_e32 v68, 0
	v_mov_b32_e32 v69, 0
	v_mov_b32_e32 v62, 0
	v_mov_b32_e32 v63, 0
	v_mov_b32_e32 v64, 0
	v_mov_b32_e32 v65, 0
	v_mov_b32_e32 v58, 0
	v_mov_b32_e32 v59, 0
	v_mov_b32_e32 v60, 0
	v_mov_b32_e32 v61, 0
	v_mov_b32_e32 v54, 0
	v_mov_b32_e32 v55, 0
	v_mov_b32_e32 v56, 0
	v_mov_b32_e32 v57, 0
	v_mov_b32_e32 v50, 0
	v_mov_b32_e32 v51, 0
	v_mov_b32_e32 v52, 0
	v_mov_b32_e32 v53, 0
	v_mov_b32_e32 v46, 0
	v_mov_b32_e32 v47, 0
	v_mov_b32_e32 v48, 0
	v_mov_b32_e32 v49, 0
	v_mov_b32_e32 v42, 0
	v_mov_b32_e32 v43, 0
	v_mov_b32_e32 v44, 0
	v_mov_b32_e32 v45, 0
	v_mov_b32_e32 v34, 0
	v_mov_b32_e32 v35, 0
	v_mov_b32_e32 v36, 0
	v_mov_b32_e32 v37, 0
	v_mov_b32_e32 v30, 0
	v_mov_b32_e32 v31, 0
	v_mov_b32_e32 v32, 0
	v_mov_b32_e32 v33, 0
	v_mov_b32_e32 v38, 0
	v_mov_b32_e32 v39, 0
	v_mov_b32_e32 v40, 0
	v_mov_b32_e32 v41, 0
	v_mov_b32_e32 v26, 0
	v_mov_b32_e32 v27, 0
	v_mov_b32_e32 v28, 0
	v_mov_b32_e32 v29, 0
	v_mov_b32_e32 v22, 0
	v_mov_b32_e32 v23, 0
	v_mov_b32_e32 v24, 0
	v_mov_b32_e32 v25, 0
	v_mov_b32_e32 v19, 0
	v_mov_b32_e32 v20, 0
	v_mov_b32_e32 v21, 0
	v_mov_b32_e32 v14, 0
	v_mov_b32_e32 v15, 0
	v_mov_b32_e32 v16, 0
	v_mov_b32_e32 v12, 0
	v_mov_b32_e32 v13, 0
	s_waitcnt vmcnt(0)
	s_waitcnt vmcnt(0) lgkmcnt(0)
	s_barrier
	global_load_lds_dwordx4 v[2:3], off
	v_add_u32_e32 v2, 0x18000, v17
	v_lshl_add_u64 v[6:7], v[6:7], 0, s[34:35]
	v_readfirstlane_b32 s15, v2
	v_lshl_add_u64 v[6:7], v[6:7], 0, v[130:131]
	s_mov_b32 m0, s15
	v_lshl_add_u64 v[2:3], v[4:5], 0, s[34:35]
	global_load_lds_dwordx4 v[6:7], off
	v_add_u32_e32 v6, 0x10000, v18
	v_lshl_add_u64 v[2:3], v[2:3], 0, v[132:133]
	v_readfirstlane_b32 s15, v6
	s_mov_b32 m0, s15
	v_lshl_add_u64 v[4:5], v[10:11], 0, s[34:35]
	global_load_lds_dwordx4 v[2:3], off
	v_add_u32_e32 v2, 0x18000, v18
	v_lshl_add_u64 v[4:5], v[4:5], 0, v[132:133]
	v_readfirstlane_b32 s15, v2
	s_mov_b32 m0, s15
	v_and_b32_e32 v134, 15, v175
	global_load_lds_dwordx4 v[4:5], off
	v_ashrrev_i32_e32 v2, 1, v175
	s_movk_i32 s15, 0xff80
	v_mov_b32_e32 v5, 0
	v_and_or_b32 v225, v2, s15, v134
	v_lshlrev_b32_e32 v224, 6, v174
	s_cmp_lt_u32 s14, 64
	v_readlane_b32 s51, v255, 37
	v_readlane_b32 s52, v255, 38
	s_cbranch_scc1 .Lgemm_skip_zero_a
	v_lshrrev_b32_e32 v10, 1, v134
	v_or_b32_e32 v2, v224, v134
	v_lshlrev_b32_e32 v182, 7, v2
	v_xor_b32_e32 v2, v223, v10
	v_lshlrev_b32_e32 v181, 7, v225
	v_lshlrev_b32_e32 v183, 4, v2
	v_or_b32_e32 v11, v181, v183
	v_or_b32_e32 v244, v182, v183
	v_lshl_add_u32 v240, v166, 1, v130
	v_lshl_add_u32 v241, v168, 1, v130
	v_lshl_add_u32 v242, v170, 1, v132
	v_lshl_add_u32 v243, v172, 1, v132
	ds_read_b128 v[150:153], v11
	ds_read_b128 v[146:149], v11 offset:2048
	ds_read_b128 v[142:145], v244 offset:32768
	ds_read_b128 v[138:141], v244 offset:34816
	ds_read_b128 v[134:137], v244 offset:36864
	ds_read_b128 v[200:203], v11 offset:4096
	ds_read_b128 v[130:133], v244 offset:38912
	ds_read_b128 v[236:239], v11 offset:6144
	s_lshr_b32 s14, s14, 6
	v_bitop3_b32 v10, v223, v10, 4 bitop3:0x36
	v_mov_b32_e32 v126, 0
	s_add_i32 s15, s14, -1
	v_lshlrev_b32_e32 v184, 4, v10
	s_mov_b32 s24, 0
	s_mov_b32 s28, 0
	v_mov_b32_e32 v161, v1
	v_lshl_add_u64 v[154:155], v[154:155], 1, v[0:1]
	v_lshl_add_u64 v[156:157], v[156:157], 1, v[0:1]
	v_lshl_add_u64 v[158:159], v[158:159], 1, v[160:161]
	v_lshl_add_u64 v[164:165], v[164:165], 1, v[160:161]
	v_readfirstlane_b32 s100, v179
	v_readfirstlane_b32 s101, v180
	v_readfirstlane_b32 s32, v178
	v_readfirstlane_b32 s41, v177
	s_lshl_b32 s32, s32, 16
	s_or_b32 s32, s32, s41
	v_mov_b32_e32 v18, v126
	v_mov_b32_e32 v17, v126
	v_mov_b32_e32 v10, v126
	v_mov_b32_e32 v11, v126
	v_mov_b32_e32 v6, v126
	v_mov_b32_e32 v7, v126
	v_mov_b32_e32 v8, v126
	v_mov_b32_e32 v9, v126
	v_mov_b32_e32 v2, v126
	v_mov_b32_e32 v3, v126
	v_mov_b32_e32 v4, v126
	v_mov_b32_e32 v5, v126
.LBB0_639:
	s_add_i32 s41, s28, 1
	s_cmp_lt_u32 s41, s14
	s_cselect_b32 s29, s41, s28
	s_and_b32 s46, s24, 0x10000
	s_lshl_b32 s34, s29, 6
	s_xor_b32 s50, s46, 0x10000
	s_lshl_b64 s[42:43], s[34:35], 1
	s_add_u32 s48, s2, s42
	s_addc_u32 s49, s3, s43
	s_add_u32 s42, s4, s42
	v_add_u32_e32 v185, s46, v181
	s_waitcnt lgkmcnt(5)
	v_mfma_f32_16x16x32_bf16 v[126:129], v[142:145], v[150:153], v[126:129]
	s_addc_u32 s43, s5, s43
	v_add_u32_e32 v227, v185, v183
	v_mfma_f32_16x16x32_bf16 v[110:113], v[142:145], v[146:149], v[110:113]
	s_add_i32 m0, s50, s100
	s_waitcnt lgkmcnt(4)
	v_mfma_f32_16x16x32_bf16 v[122:125], v[138:141], v[150:153], v[122:125]
	s_add_i32 s28, s28, 2
	s_min_i32 s28, s28, s15
	s_lshl_b32 s28, s28, 6
	v_mfma_f32_16x16x32_bf16 v[106:109], v[138:141], v[146:149], v[106:109]
	global_load_lds_dwordx4 v154, s[48:49]
	s_add_i32 m0, m0, 0x8000
	s_waitcnt lgkmcnt(3)
	v_mfma_f32_16x16x32_bf16 v[118:121], v[134:137], v[150:153], v[118:121]
	v_mfma_f32_16x16x32_bf16 v[102:105], v[134:137], v[146:149], v[102:105]
	global_load_lds_dwordx4 v156, s[42:43]
	s_add_i32 m0, s50, s101
	s_waitcnt lgkmcnt(1)
	v_mfma_f32_16x16x32_bf16 v[114:117], v[130:133], v[150:153], v[114:117]
	ds_read_b128 v[150:153], v227 offset:8192
	v_mfma_f32_16x16x32_bf16 v[98:101], v[130:133], v[146:149], v[98:101]
	ds_read_b128 v[146:149], v227 offset:10240
	v_mfma_f32_16x16x32_bf16 v[94:97], v[142:145], v[200:203], v[94:97]
	v_mfma_f32_16x16x32_bf16 v[90:93], v[138:141], v[200:203], v[90:93]
	global_load_lds_dwordx4 v158, s[48:49]
	s_add_i32 m0, m0, 0x8000
	v_mfma_f32_16x16x32_bf16 v[86:89], v[134:137], v[200:203], v[86:89]
	v_mfma_f32_16x16x32_bf16 v[82:85], v[130:133], v[200:203], v[82:85]
	ds_read_b128 v[200:203], v227 offset:12288
	v_bitop3_b32 v244, s24, v182, v212 bitop3:0xce
	s_waitcnt lgkmcnt(3)
	v_mfma_f32_16x16x32_bf16 v[78:81], v[142:145], v[236:239], v[78:81]
	global_load_lds_dwordx4 v164, s[42:43]
	v_add_u32_e32 v233, v244, v183
	v_mfma_f32_16x16x32_bf16 v[74:77], v[138:141], v[236:239], v[74:77]
	v_mfma_f32_16x16x32_bf16 v[70:73], v[134:137], v[236:239], v[70:73]
	v_or_b32_e32 v228, s46, v182
	s_ashr_i32 s29, s28, 31
	v_mfma_f32_16x16x32_bf16 v[66:69], v[130:133], v[236:239], v[66:69]
	ds_read_b128 v[236:239], v227 offset:14336
	s_waitcnt lgkmcnt(3)
	v_mfma_f32_16x16x32_bf16 v[62:65], v[142:145], v[150:153], v[62:65]
	v_add3_u32 v234, s50, v181, v183
	v_add_u32_e32 v228, v228, v184
	v_mfma_f32_16x16x32_bf16 v[58:61], v[138:141], v[150:153], v[58:61]
	v_add_u32_e32 v229, v185, v184
	v_mfma_f32_16x16x32_bf16 v[54:57], v[134:137], v[150:153], v[54:57]
	v_mfma_f32_16x16x32_bf16 v[50:53], v[130:133], v[150:153], v[50:53]
	ds_read_b128 v[150:153], v229
	s_waitcnt lgkmcnt(3)
	v_mfma_f32_16x16x32_bf16 v[46:49], v[142:145], v[146:149], v[46:49]
	v_mfma_f32_16x16x32_bf16 v[42:45], v[138:141], v[146:149], v[42:45]
	v_mfma_f32_16x16x32_bf16 v[34:37], v[134:137], v[146:149], v[34:37]
	v_mfma_f32_16x16x32_bf16 v[30:33], v[130:133], v[146:149], v[30:33]
	ds_read_b128 v[146:149], v229 offset:2048
	s_waitcnt lgkmcnt(3)
	v_mfma_f32_16x16x32_bf16 v[38:41], v[142:145], v[200:203], v[38:41]
	s_waitcnt lgkmcnt(2)
	v_mfma_f32_16x16x32_bf16 v[14:17], v[142:145], v[236:239], v[14:17]
	ds_read_b128 v[142:145], v228 offset:32768
	v_mfma_f32_16x16x32_bf16 v[26:29], v[138:141], v[200:203], v[26:29]
	v_mfma_f32_16x16x32_bf16 v[10:13], v[138:141], v[236:239], v[10:13]
	ds_read_b128 v[138:141], v228 offset:34816
	v_mfma_f32_16x16x32_bf16 v[22:25], v[134:137], v[200:203], v[22:25]
	v_mfma_f32_16x16x32_bf16 v[6:9], v[134:137], v[236:239], v[6:9]
	ds_read_b128 v[134:137], v228 offset:36864
	v_mfma_f32_16x16x32_bf16 v[18:21], v[130:133], v[200:203], v[18:21]
	ds_read_b128 v[200:203], v229 offset:4096
	v_mfma_f32_16x16x32_bf16 v[2:5], v[130:133], v[236:239], v[2:5]
	ds_read_b128 v[130:133], v228 offset:38912
	ds_read_b128 v[236:239], v229 offset:6144
	s_waitcnt lgkmcnt(5)
	v_mfma_f32_16x16x32_bf16 v[126:129], v[142:145], v[150:153], v[126:129]
	v_mfma_f32_16x16x32_bf16 v[110:113], v[142:145], v[146:149], v[110:113]
	s_waitcnt lgkmcnt(4)
	v_mfma_f32_16x16x32_bf16 v[122:125], v[138:141], v[150:153], v[122:125]
	v_mfma_f32_16x16x32_bf16 v[106:109], v[138:141], v[146:149], v[106:109]
	s_waitcnt lgkmcnt(3)
	v_mfma_f32_16x16x32_bf16 v[118:121], v[134:137], v[150:153], v[118:121]
	v_mfma_f32_16x16x32_bf16 v[102:105], v[134:137], v[146:149], v[102:105]
	s_waitcnt lgkmcnt(1)
	v_mfma_f32_16x16x32_bf16 v[114:117], v[130:133], v[150:153], v[114:117]
	ds_read_b128 v[150:153], v229 offset:8192
	v_mfma_f32_16x16x32_bf16 v[98:101], v[130:133], v[146:149], v[98:101]
	ds_read_b128 v[146:149], v229 offset:10240
	v_mfma_f32_16x16x32_bf16 v[94:97], v[142:145], v[200:203], v[94:97]
	v_mfma_f32_16x16x32_bf16 v[90:93], v[138:141], v[200:203], v[90:93]
	v_mfma_f32_16x16x32_bf16 v[86:89], v[134:137], v[200:203], v[86:89]
	v_mfma_f32_16x16x32_bf16 v[82:85], v[130:133], v[200:203], v[82:85]
	ds_read_b128 v[200:203], v229 offset:12288
	s_waitcnt lgkmcnt(3)
	v_mfma_f32_16x16x32_bf16 v[78:81], v[142:145], v[236:239], v[78:81]
	v_mfma_f32_16x16x32_bf16 v[74:77], v[138:141], v[236:239], v[74:77]
	v_mfma_f32_16x16x32_bf16 v[70:73], v[134:137], v[236:239], v[70:73]
	s_lshl_b64 s[28:29], s[28:29], 1
	s_add_u32 s48, s2, s28
	s_addc_u32 s49, s3, s29
	s_add_u32 s42, s4, s28
	s_addc_u32 s43, s5, s29
	s_and_b32 m0, s32, 0xffff
	v_mfma_f32_16x16x32_bf16 v[66:69], v[130:133], v[236:239], v[66:69]
	ds_read_b128 v[236:239], v229 offset:14336
	s_add_i32 m0, m0, s46
	s_waitcnt lgkmcnt(3)
	v_mfma_f32_16x16x32_bf16 v[62:65], v[142:145], v[150:153], v[62:65]
	v_mfma_f32_16x16x32_bf16 v[58:61], v[138:141], v[150:153], v[58:61]
	v_mfma_f32_16x16x32_bf16 v[54:57], v[134:137], v[150:153], v[54:57]
	v_mfma_f32_16x16x32_bf16 v[50:53], v[130:133], v[150:153], v[50:53]
	s_waitcnt vmcnt(0) lgkmcnt(0)
	s_barrier
	ds_read_b128 v[150:153], v234
	v_mfma_f32_16x16x32_bf16 v[46:49], v[142:145], v[146:149], v[46:49]
	global_load_lds_dwordx4 v240, s[48:49]
	s_add_i32 m0, m0, 0x8000
	v_mfma_f32_16x16x32_bf16 v[42:45], v[138:141], v[146:149], v[42:45]
	v_mfma_f32_16x16x32_bf16 v[34:37], v[134:137], v[146:149], v[34:37]
	global_load_lds_dwordx4 v241, s[42:43]
	s_lshr_b32 m0, s32, 16
	v_mfma_f32_16x16x32_bf16 v[30:33], v[130:133], v[146:149], v[30:33]
	ds_read_b128 v[146:149], v234 offset:2048
	s_add_i32 m0, m0, s46
	v_mfma_f32_16x16x32_bf16 v[38:41], v[142:145], v[200:203], v[38:41]
	v_mfma_f32_16x16x32_bf16 v[14:17], v[142:145], v[236:239], v[14:17]
	ds_read_b128 v[142:145], v233 offset:32768
	global_load_lds_dwordx4 v242, s[48:49]
	s_add_i32 m0, m0, 0x8000
	v_mfma_f32_16x16x32_bf16 v[26:29], v[138:141], v[200:203], v[26:29]
	v_mfma_f32_16x16x32_bf16 v[10:13], v[138:141], v[236:239], v[10:13]
	ds_read_b128 v[138:141], v233 offset:34816
	global_load_lds_dwordx4 v243, s[42:43]
	v_mfma_f32_16x16x32_bf16 v[22:25], v[134:137], v[200:203], v[22:25]
	v_mfma_f32_16x16x32_bf16 v[6:9], v[134:137], v[236:239], v[6:9]
	ds_read_b128 v[134:137], v233 offset:36864
	v_mfma_f32_16x16x32_bf16 v[18:21], v[130:133], v[200:203], v[18:21]
	ds_read_b128 v[200:203], v234 offset:4096
	v_mfma_f32_16x16x32_bf16 v[2:5], v[130:133], v[236:239], v[2:5]
	ds_read_b128 v[130:133], v233 offset:38912
	ds_read_b128 v[236:239], v234 offset:6144
	s_add_i32 s24, s24, 0x10000
	s_cmp_eq_u32 s14, s41
	s_mov_b32 s28, s41
	s_cbranch_scc0 .LBB0_639
